# per-unit class lookup via scalar load (no VMEM drain between attention units); redundant drain at MLA unit start removed
# baseline (speedup 1.0000x reference)
; template <int MODE>
; DI void attn_unit(LAS unsigned char* lds, const bf16_t* Qg, int ldq, const bf16_t* Kg, int ldk, const bf16_t* VTg, int ldvt, bf16_t* Og, int ldo,
;                   int q0, int NT, const float* gout, const float* relb, float lam, float osc, const float* qgain) {
;     ...
;         const bf16_t* qp = Qg + (size_t)qrow * ldq + mm * 64 + 8 * hi;
; #pragma unroll
;         for (int s = 0; s < NS; ++s) qf[s] = *(const bf16x8*)(qp + 16 * s);
; __global__ void __launch_bounds__(512, 2) mk_fwd(Args a) {
;     ...
;                 { const unsigned char tab[32] = {15, 14, 16 + 7, 13, 12, 16 + 6, 11, 10, 16 + 5, 9, 8, 16 + 4, 7, 16 + 3, 6, 32 + 7, 32 + 6, 32 + 5, 32 + 4, 32 + 3, 32 + 2, 32 + 1,
;                                                  5, 16 + 2, 4, 3, 32 + 0, 16 + 1, 2, 1, 16 + 0, 0}; code = tab[cls]; }
;                 const int typ = code >> 4, lvl = code & 15, grp = typ == 1 ? 0 : (typ == 2 ? 3 : 1);
;                 if (PROBE_ATT_ONLY >= 0 && dup && typ != PROBE_ATT_ONLY) continue;
;                 const size_t rb = (size_t)b * SEQ;
;                 if (grp == 0) at::attn_unit<1>(lds, QM + rb * 512 + h * 96, 512, KM + rb * 384 + h * 96, 384, VTM + (size_t)(h * 64) * MT + rb, MT, Y + rb * DM + 768 + h * 64, DM,
;                                                256 * lvl, 4 * lvl + 4, a.in[16] + l * 64, nullptr, 0.f, 1.f, a.in[14] + l * 96);
;                 else if (grp == 3) { const int hp = h >> 1, i = 2 * lvl + (h & 1);
;                     at::attn_unit<2>(lds, PROJ + rb * LDP + 1024 + hp * 128, LDP, PROJ + rb * LDP + 1280 + hp * 128, LDP, VT + (size_t)(512 + hp * 128) * MT + rb, MT, Y + rb * DM + 512 + hp * 128, DM,
;                                      128 * i, 2 * i + 2, a.in[9] + l * 64, nullptr, 0.f, 1.f, nullptr); }
.LBB0_103:
	s_mov_b64 s[4:5], -1
	s_and_b64 vcc, exec, s[0:1]
	s_cbranch_vccz .LBB0_97
	v_writelane_b32 v254, s6, 36
	s_lshr_b32 s16, s2, 2
	s_and_b32 s0, s2, 3
	s_ashr_i32 s4, s3, 31
	v_writelane_b32 v254, s0, 18
	s_getpc_b64 s[0:1]
	s_add_u32 s0, s0, __const._Z6mk_fwd4Args.tab@rel32@lo+4
	s_addc_u32 s1, s1, __const._Z6mk_fwd4Args.tab@rel32@hi+12
	s_and_b32 s4, s3, 28
	s_load_dword s0, s[0:1], s4
	s_and_b32 s4, s3, 3
	s_lshl_b32 s4, s4, 3
	s_waitcnt lgkmcnt(0)
	s_lshr_b32 s0, s0, s4
	s_and_b32 s0, s0, 0xff
	s_lshr_b32 s1, s0, 4
	s_and_b32 s29, s0, 15
	s_cmp_eq_u32 s1, 2
	s_cselect_b32 s0, 3, 1
	s_cmp_lg_u32 s1, 1
	s_cselect_b32 s3, s0, 0
	s_lshl_b64 s[0:1], s[16:17], 11
	v_writelane_b32 v254, s0, 38
	s_cmp_gt_i32 s3, 2
	s_nop 0
	v_writelane_b32 v254, s1, 39
	s_mov_b64 s[0:1], -1
	s_cbranch_scc0 .LBB0_142
	v_writelane_b32 v254, s3, 40
	s_lshl_b32 s0, s29, 1
	s_and_b32 s3, s2, 1
	s_or_b32 s12, s0, s3
	s_lshl_b64 s[4:5], s[16:17], 23
	v_readlane_b32 s0, v254, 2
	v_readlane_b32 s1, v254, 3
	s_add_u32 s0, s0, s4
	v_readlane_b32 s6, v254, 18
	s_addc_u32 s1, s1, s5
	s_lshl_b32 s6, s6, 6
	s_and_b32 s14, s6, 0x80
	s_lshl_b32 s6, s14, 1
	v_mov_b32_e32 v14, v229
	v_writelane_b32 v254, s6, 42
	s_add_u32 s6, s0, s6
	s_addc_u32 s7, s1, 0
	v_readfirstlane_b32 s0, v14
	s_ashr_i32 s11, s0, 6
	s_ashr_i32 s10, s0, 8
	s_lshl_b32 s0, s11, 5
	s_lshl_b32 s15, s12, 7
	s_and_b32 s0, s0, 0x60
	v_and_b32_e32 v15, 31, v14
	s_or_b32 s13, s0, s15
	v_or_b32_e32 v0, s13, v15
	v_lshlrev_b32_e32 v2, 12, v0
	v_mov_b32_e32 v3, v1
	s_lshl_b32 s22, s10, 6
	v_bfe_u32 v16, v14, 5, 1
	v_lshl_add_u64 v[2:3], s[6:7], 0, v[2:3]
	s_ashr_i32 s23, s22, 31
	v_lshl_add_u64 v[4:5], s[22:23], 1, v[2:3]
	v_lshlrev_b32_e32 v2, 4, v16
	v_mov_b32_e32 v3, v1
	v_lshl_add_u64 v[4:5], v[4:5], 0, v[2:3]
	flat_load_dwordx4 v[66:69], v[4:5] offset:2048
	flat_load_dwordx4 v[70:73], v[4:5] offset:2080
	flat_load_dwordx4 v[74:77], v[4:5] offset:2112
	flat_load_dwordx4 v[78:81], v[4:5] offset:2144
	s_movk_i32 s0, 0x400
	v_ashrrev_i32_e32 v3, 31, v14
	s_or_b32 s18, s15, 64
	v_cmp_gt_i32_e64 s[40:41], s0, v14
	v_lshrrev_b32_e32 v3, 28, v3
	s_and_saveexec_b64 s[0:1], s[40:41]
	s_cbranch_execz .LBB0_107
	v_add_u32_e32 v4, v14, v3
	v_and_b32_e32 v5, 0x1ffffff0, v4
	v_ashrrev_i32_e32 v4, 4, v4
	v_add_u32_e32 v4, s18, v4
	v_sub_u32_e32 v6, v14, v5
	v_ashrrev_i32_e32 v5, 31, v4
	v_lshlrev_b64 v[4:5], 12, v[4:5]
	v_lshlrev_b32_e32 v6, 3, v6
	v_lshl_add_u64 v[4:5], s[6:7], 0, v[4:5]
	v_ashrrev_i32_e32 v7, 31, v6
	v_lshl_add_u64 v[4:5], v[6:7], 1, v[4:5]
	flat_load_dwordx4 v[82:85], v[4:5] offset:2560

; DI float shx(float v, int mask, int lane) { return __builtin_bit_cast(float, __builtin_amdgcn_ds_bpermute((lane ^ mask) << 2, __builtin_bit_cast(int, v))); }
; DI float bflo(unsigned w) { return __uint_as_float(w << 16); }
; DI float bfhi(unsigned w) { return __uint_as_float(w & 0xffff0000u); }
; template <int MODE>
; DI void attn_unit(LAS unsigned char* lds, const bf16_t* Qg, int ldq, const bf16_t* Kg, int ldk, const bf16_t* VTg, int ldvt, bf16_t* Og, int ldo,
;                   int q0, int NT, const float* gout, const float* relb, float lam, float osc, const float* qgain) {
;     ...
;         const bf16_t* qp = Qg + (size_t)qrow * ldq + mm * 64 + 8 * hi;
; #pragma unroll
;         for (int s = 0; s < NS; ++s) qf[s] = *(const bf16x8*)(qp + 16 * s);
;         if (MODE == 1) {
;             float ss = 0.f; float f[NS][8];
; #pragma unroll
;             for (int s = 0; s < NS; ++s) { const u32x4 w = __builtin_bit_cast(u32x4, qf[s]);
; #pragma unroll
;                 for (int j = 0; j < 4; ++j) { f[s][2 * j] = bflo(w[j]); f[s][2 * j + 1] = bfhi(w[j]); ss += f[s][2 * j] * f[s][2 * j] + f[s][2 * j + 1] * f[s][2 * j + 1]; } }
;             ss += shx(ss, 32, lane);
;             const float rs = rsqrtf(ss * (1.f / 96.f) + EPS);
.LBB0_210:
	s_lshl_b64 s[0:1], s[16:17], 21
	v_readlane_b32 s2, v254, 6
	v_readlane_b32 s3, v254, 7
	s_add_u32 s0, s2, s0
	v_readlane_b32 s2, v254, 18
	s_addc_u32 s1, s3, s1
	s_mulk_i32 s2, 0xc0
	s_add_u32 s0, s0, s2
	s_addc_u32 s1, s1, 0
	s_mul_i32 s6, s16, 0x180000
	v_readlane_b32 s4, v254, 8
	s_mul_hi_u32 s7, s16, 0x180000
	v_readlane_b32 s5, v254, 9
	s_add_u32 s3, s4, s6
	s_addc_u32 s5, s5, s7
	v_mov_b32_e32 v146, v229
	s_add_u32 s4, s3, s2
	s_addc_u32 s5, s5, 0
	v_readfirstlane_b32 s3, v146
	s_ashr_i32 s8, s3, 6
	s_lshl_b32 s2, s29, 8
	s_lshl_b32 s10, s8, 5
	v_and_b32_e32 v147, 31, v146
	s_add_i32 s10, s10, s2
	v_or_b32_e32 v130, s10, v147
	v_ashrrev_i32_e32 v131, 31, v130
	v_bfe_u32 v114, v146, 5, 1
	v_lshlrev_b64 v[2:3], 10, v[130:131]
	v_lshl_add_u64 v[2:3], s[0:1], 0, v[2:3]
	v_lshlrev_b32_e32 v128, 4, v114
	v_mov_b32_e32 v129, v1
	v_lshl_add_u64 v[38:39], v[2:3], 0, v[128:129]
	flat_load_dwordx4 v[34:37], v[38:39] offset:128
	flat_load_dwordx4 v[30:33], v[38:39] offset:160
	flat_load_dwordx4 v[26:29], v[38:39] offset:96
	flat_load_dwordx4 v[50:53], v[38:39] offset:64
	v_readlane_b32 s0, v254, 28
	v_and_b32_e32 v0, 32, v146
	v_readlane_b32 s1, v254, 29
	s_nop 4
	global_load_dwordx4 v[6:9], v0, s[0:1] offset:272
	global_load_dwordx4 v[14:17], v0, s[0:1] offset:256
	flat_load_dwordx4 v[54:57], v[38:39] offset:32
	global_load_dwordx4 v[2:5], v0, s[0:1] offset:336
	global_load_dwordx4 v[10:13], v0, s[0:1] offset:320
	global_load_dwordx4 v[18:21], v0, s[0:1] offset:208
	global_load_dwordx4 v[22:25], v0, s[0:1] offset:192
	flat_load_dwordx4 v[96:99], v[38:39]
	v_and_b32_e32 v160, 63, v146
	v_lshlrev_b32_e32 v40, 2, v160
	v_xor_b32_e32 v129, 0x80, v40
	s_waitcnt vmcnt(0) lgkmcnt(0)
	v_and_b32_e32 v63, 0xffff0000, v37
	v_and_b32_e32 v59, 0xffff0000, v33
	v_and_b32_e32 v67, 0xffff0000, v36
	v_and_b32_e32 v61, 0xffff0000, v32
	v_and_b32_e32 v71, 0xffff0000, v35
	v_and_b32_e32 v65, 0xffff0000, v31
	v_and_b32_e32 v73, 0xffff0000, v34
	v_and_b32_e32 v69, 0xffff0000, v30
	v_lshlrev_b32_e32 v62, 16, v37
	v_lshlrev_b32_e32 v58, 16, v33
	v_lshlrev_b32_e32 v66, 16, v36
	v_lshlrev_b32_e32 v60, 16, v32
	v_lshlrev_b32_e32 v70, 16, v35
	v_lshlrev_b32_e32 v64, 16, v31
	v_lshlrev_b32_e32 v72, 16, v34
	v_lshlrev_b32_e32 v68, 16, v30
	v_lshlrev_b32_e32 v74, 16, v29
	v_and_b32_e32 v75, 0xffff0000, v29
	v_lshlrev_b32_e32 v78, 16, v28
	v_and_b32_e32 v79, 0xffff0000, v28
	v_mov_b32_e32 v28, v63
	v_mov_b32_e32 v29, v67
	v_mov_b32_e32 v32, v59
	v_mov_b32_e32 v33, v61
	v_mov_b32_e32 v36, v71
	v_mov_b32_e32 v37, v73
	v_mov_b32_e32 v40, v65
	v_mov_b32_e32 v41, v69
	v_lshlrev_b32_e32 v80, 16, v27
	v_and_b32_e32 v81, 0xffff0000, v27
	v_lshlrev_b32_e32 v82, 16, v26
	v_and_b32_e32 v83, 0xffff0000, v26
	v_mov_b32_e32 v26, v62
	v_mov_b32_e32 v27, v66
	v_mov_b32_e32 v30, v58
	v_mov_b32_e32 v31, v60
	v_mov_b32_e32 v34, v70
	v_mov_b32_e32 v35, v72
	v_mov_b32_e32 v38, v64
	v_mov_b32_e32 v39, v68
	v_mov_b32_e32 v42, v75
	v_mov_b32_e32 v43, v79
	v_pk_mul_f32 v[28:29], v[28:29], v[28:29]
	v_pk_mul_f32 v[32:33], v[32:33], v[32:33]
	v_pk_mul_f32 v[36:37], v[36:37], v[36:37]
	v_pk_mul_f32 v[40:41], v[40:41], v[40:41]
	v_pk_mul_f32 v[84:85], v[42:43], v[42:43]
	v_pk_fma_f32 v[112:113], v[26:27], v[26:27], v[28:29]
	v_pk_fma_f32 v[116:117], v[30:31], v[30:31], v[32:33]
	v_pk_fma_f32 v[118:119], v[34:35], v[34:35], v[36:37]
	v_pk_fma_f32 v[120:121], v[38:39], v[38:39], v[40:41]
	global_load_dwordx4 v[26:29], v0, s[0:1] offset:144
	global_load_dwordx4 v[30:33], v0, s[0:1] offset:128
	global_load_dwordx4 v[34:37], v0, s[0:1] offset:80
	global_load_dwordx4 v[38:41], v0, s[0:1] offset:64
	global_load_dwordx4 v[42:45], v0, s[0:1] offset:16
	global_load_dwordx4 v[46:49], v0, s[0:1]
	v_lshlrev_b32_e32 v92, 16, v57
	v_and_b32_e32 v93, 0xffff0000, v57
	v_lshlrev_b32_e32 v94, 16, v56
	v_and_b32_e32 v95, 0xffff0000, v56
	v_lshlrev_b32_e32 v56, 16, v55
	v_and_b32_e32 v57, 0xffff0000, v55
	v_lshlrev_b32_e32 v104, 16, v54
	v_and_b32_e32 v105, 0xffff0000, v54
	v_lshlrev_b32_e32 v54, 16, v99
	v_and_b32_e32 v55, 0xffff0000, v99
	v_lshlrev_b32_e32 v88, 16, v51
	v_and_b32_e32 v89, 0xffff0000, v51
	v_lshlrev_b32_e32 v90, 16, v50
	v_and_b32_e32 v91, 0xffff0000, v50
	v_lshlrev_b32_e32 v108, 16, v97
	v_and_b32_e32 v109, 0xffff0000, v97
	v_lshlrev_b32_e32 v110, 16, v96
	v_and_b32_e32 v111, 0xffff0000, v96
	v_pk_mul_f32 v[50:51], v[54:55], v[54:55]
	v_lshlrev_b32_e32 v106, 16, v98
	v_and_b32_e32 v107, 0xffff0000, v98
	v_pk_mul_f32 v[96:97], v[108:109], v[108:109]
	v_add_f32_e32 v0, v50, v51
	v_pk_mul_f32 v[50:51], v[110:111], v[110:111]
	v_add_f32_e32 v96, v96, v97
	v_add_f32_e32 v97, v50, v51
	v_pk_mul_f32 v[50:51], v[106:107], v[106:107]
	v_add_f32_e32 v96, v97, v96
	v_add_f32_e32 v97, v50, v51
	v_add_f32_e32 v96, v97, v96
	v_add_f32_e32 v0, v0, v96
	v_pk_mul_f32 v[96:97], v[104:105], v[104:105]
	v_pk_mul_f32 v[50:51], v[90:91], v[90:91]
	v_add_f32_e32 v96, v96, v97
	v_add_f32_e32 v0, v96, v0
	v_pk_mul_f32 v[96:97], v[56:57], v[56:57]
	v_mov_b32_e32 v76, v74
	v_add_f32_e32 v96, v96, v97
	v_add_f32_e32 v0, v96, v0
	v_pk_mul_f32 v[96:97], v[94:95], v[94:95]
	v_mov_b32_e32 v77, v78
	v_add_f32_e32 v96, v96, v97
	v_add_f32_e32 v0, v96, v0
	v_pk_mul_f32 v[96:97], v[92:93], v[92:93]
	v_lshlrev_b32_e32 v86, 16, v52
	v_add_f32_e32 v96, v96, v97
	v_and_b32_e32 v87, 0xffff0000, v52
	v_pk_mul_f32 v[124:125], v[88:89], v[88:89]
	v_add_f32_e32 v0, v96, v0
	v_add_f32_e32 v50, v50, v51
	v_pk_fma_f32 v[76:77], v[76:77], v[76:77], v[84:85]
	v_lshlrev_b32_e32 v84, 16, v53
	v_and_b32_e32 v85, 0xffff0000, v53
	v_pk_mul_f32 v[52:53], v[86:87], v[86:87]
	v_add_f32_e32 v0, v50, v0
	v_add_f32_e32 v50, v124, v125
	v_pk_mul_f32 v[122:123], v[84:85], v[84:85]
	v_add_f32_e32 v0, v50, v0
	v_add_f32_e32 v50, v52, v53
	v_pk_mul_f32 v[102:103], v[82:83], v[82:83]
	v_add_f32_e32 v0, v50, v0
	v_add_f32_e32 v50, v122, v123
	v_pk_mul_f32 v[100:101], v[80:81], v[80:81]
	v_add_f32_e32 v0, v50, v0
	v_add_f32_e32 v50, v102, v103
	v_add_f32_e32 v0, v50, v0
	v_add_f32_e32 v50, v100, v101
	v_add_f32_e32 v0, v50, v0
	v_add_f32_e32 v0, v77, v0
	v_add_f32_e32 v0, v76, v0
	v_add_f32_e32 v0, v119, v0
	v_add_f32_e32 v0, v118, v0
	v_add_f32_e32 v0, v113, v0
	v_add_f32_e32 v0, v112, v0
	v_add_f32_e32 v0, v121, v0
	v_add_f32_e32 v0, v120, v0
	v_add_f32_e32 v0, v117, v0
	v_add_f32_e32 v115, v116, v0
	ds_bpermute_b32 v116, v129, v115
	s_movk_i32 s0, 0x300
	v_cmp_gt_i32_e64 s[38:39], s0, v146
	s_mov_b32 s0, 0x2aaaaaab
	v_mul_hi_i32 v0, v146, s0
	v_lshrrev_b32_e32 v150, 31, v0
	v_ashrrev_i32_e32 v151, 1, v0
	s_and_saveexec_b64 s[0:1], s[38:39]
	s_cbranch_execz .LBB0_212
	v_add_u32_e32 v0, v151, v150
	v_mul_lo_u32 v50, v0, 12
	v_sub_u32_e32 v52, v146, v50
	v_mov_b64_e32 v[50:51], s[4:5]
	s_movk_i32 s2, 0x300
	v_lshlrev_b32_e32 v52, 3, v52
	v_mad_i64_i32 v[50:51], s[2:3], v0, s2, v[50:51]
	v_ashrrev_i32_e32 v53, 31, v52
	v_lshl_add_u64 v[50:51], v[52:53], 1, v[50:51]
	flat_load_dwordx4 v[96:99], v[50:51]
